# v41 + first counted wait of the peeled K-iteration no longer drains the epilogue stores (vmcnt(6+stores)); equalising never-read loads behind the prologue in P2/P5/P12
# baseline (speedup 1.0000x reference)
.LBB0_563:
	s_add_u32 s0, s30, 0x1b00000
	s_addc_u32 s1, s31, 0
	s_mov_b64 s[4:5], 0x80
	s_add_u32 s8, s34, 0x40080
	v_lshl_add_u64 v[2:3], v[2:3], 0, s[4:5]
	s_addc_u32 s9, s35, 0
	s_add_i32 m0, s53, 0x18000
	v_lshl_add_u64 v[4:5], v[4:5], 0, s[4:5]
	s_waitcnt vmcnt(0)
	s_barrier
	global_load_lds_dwordx4 v[2:3], off
	s_add_i32 m0, s53, 0x1a000
	s_add_i32 s68, s53, 0x8000
	v_lshl_add_u64 v[6:7], v[6:7], 0, s[4:5]
	global_load_lds_dwordx4 v[4:5], off
	s_mov_b32 m0, s68
	s_add_i32 s69, s53, 0xa000
	v_lshl_add_u64 v[8:9], v[8:9], 0, s[4:5]
	global_load_lds_dwordx4 v[6:7], off
	s_mov_b32 m0, s69
	s_waitcnt vmcnt(0)
	v_lshl_add_u64 v[14:15], s[8:9], 0, v[134:135]
	global_load_lds_dwordx4 v[8:9], off
	s_add_i32 m0, s53, 0x1c000
	v_lshl_add_u64 v[16:17], s[8:9], 0, v[130:131]
	global_load_lds_dwordx4 v[14:15], off
	s_add_i32 m0, s53, 0x1e000
	v_lshlrev_b32_e32 v3, 4, v1
	global_load_lds_dwordx4 v[16:17], off
	v_lshlrev_b32_e32 v4, 6, v170
	s_movk_i32 s7, 0x3c0
	v_lshlrev_b32_e32 v6, 2, v148
	v_and_or_b32 v4, v4, s7, v3
	v_lshlrev_b32_e32 v5, 2, v170
	s_sext_i32_i16 s15, s2
	s_and_b32 s2, s6, 3
	v_lshl_or_b32 v149, s3, 6, v148
	v_lshl_or_b32 v3, v148, 6, v3
	s_lshl_b32 s3, s3, 13
	v_and_b32_e32 v6, 32, v6
	v_and_b32_e32 v5, 32, v5
	v_bitop3_b32 v3, v3, s3, v6 bitop3:0xde
	s_lshl_b32 s3, s2, 12
	v_bitop3_b32 v150, s3, v4, v5 bitop3:0xf6
	v_lshlrev_b32_e32 v4, 8, v170
	v_and_b32_e32 v4, 0x38000, v4
	v_lshlrev_b32_e32 v5, 11, v13
	v_or3_b32 v4, v11, v4, v5
	v_add_u32_e32 v140, v4, v12
	v_lshlrev_b32_e32 v4, 4, v10
	v_lshlrev_b32_e32 v2, 3, v1
	s_waitcnt vmcnt(6)
	v_and_b32_e32 v4, 0x78000, v4
	v_lshl_or_b32 v2, s2, 5, v2
	v_or3_b32 v4, v11, v4, v5
	s_add_i32 s72, 0, 0x10000
	s_add_i32 s73, 0, 0x14000
	s_ashr_i32 s70, s22, 31
	s_mov_b32 s71, s22
	v_mov_b32_e32 v141, v139
	v_add_u32_e32 v142, v4, v12
	v_mov_b32_e32 v143, v139
	v_mov_b64_e32 v[144:145], 0xc60
	v_mov_b64_e32 v[146:147], 0xc5f
	v_add_u32_e32 v151, s72, v150
	v_add_u32_e32 v152, 0, v3
	v_add_u32_e32 v153, s73, v150
	s_movk_i32 s74, 0x1600
	v_lshlrev_b32_e32 v138, 1, v2
	s_barrier
	global_load_dword v255, v[16:17], off
	global_load_dword v255, v[16:17], off
	global_load_dword v255, v[16:17], off
	global_load_dword v255, v[16:17], off
	global_load_dword v255, v[16:17], off
	global_load_dword v255, v[16:17], off
	global_load_dword v255, v[16:17], off
	global_load_dword v255, v[16:17], off

.LBB0_566:
	s_ashr_i32 s9, s8, 31
	v_cmp_lt_i64_e32 vcc, s[10:11], v[144:145]
	s_lshl_b64 s[10:11], s[8:9], 19
	s_add_u32 s10, s40, s10
	s_addc_u32 s11, s41, s11
	s_and_b64 s[12:13], vcc, exec
	s_cselect_b32 s9, s11, s17
	s_cselect_b32 s75, s10, s16
	s_ashr_i32 s7, s6, 31
	s_lshl_b64 s[12:13], s[6:7], 19
	s_add_u32 s12, s48, s12
	s_addc_u32 s13, s49, s13
	s_and_b64 s[18:19], vcc, exec
	s_cselect_b32 s7, s13, s35
	s_cselect_b32 s76, s12, s34
	s_add_u32 s16, s16, 0x40080
	s_addc_u32 s17, s17, 0
	s_add_u32 s77, s34, 0x100
	s_addc_u32 s78, s35, 0
	s_mov_b32 s79, -2
	ds_read_b128 v[154:157], v151
	ds_read_b128 v[158:161], v151 offset:1024
	ds_read_b128 v[162:165], v151 offset:2048
	ds_read_b128 v[166:169], v151 offset:3072
	s_add_u32 s18, s16, 0xfffc0080
	s_addc_u32 s19, s17, -1
	s_cmp_eq_u32 s79, 12
	s_cselect_b32 s19, s9, s19
	s_cselect_b32 s18, s75, s18
	s_cselect_b32 s35, s7, s78
	s_cselect_b32 s34, s76, s77
	v_lshl_add_u64 v[172:173], s[16:17], 0, v[140:141]
	s_add_i32 m0, s53, 0xc000
	ds_read_b128 v[176:179], v152
	ds_read_b128 v[180:183], v152 offset:1024
	ds_read_b128 v[184:187], v152 offset:2048
	ds_read_b128 v[188:191], v152 offset:3072
	ds_read_b128 v[192:195], v152 offset:4096
	ds_read_b128 v[196:199], v152 offset:5120
	ds_read_b128 v[200:203], v152 offset:6144
	ds_read_b128 v[204:207], v152 offset:7168
	global_load_lds_dwordx4 v[172:173], off
	v_lshl_add_u64 v[172:173], s[16:17], 0, v[142:143]
	s_add_i32 m0, s53, 0xe000
	s_nop 0
	global_load_lds_dwordx4 v[172:173], off
	ds_read_b128 v[208:211], v153
	ds_read_b128 v[212:215], v153 offset:1024
	ds_read_b128 v[216:219], v153 offset:2048
	ds_read_b128 v[220:223], v153 offset:3072
	s_waitcnt lgkmcnt(0)
	s_setprio 1
	s_barrier
	v_mfma_f32_16x16x32_bf16 v[126:129], v[154:157], v[176:179], 0
	v_mfma_f32_16x16x32_bf16 v[122:125], v[162:165], v[176:179], 0
	v_mfma_f32_16x16x32_bf16 v[110:113], v[154:157], v[184:187], 0
	v_mfma_f32_16x16x32_bf16 v[106:109], v[162:165], v[184:187], 0
	v_mfma_f32_16x16x32_bf16 v[94:97], v[154:157], v[192:195], 0
	v_mfma_f32_16x16x32_bf16 v[90:93], v[162:165], v[192:195], 0
	v_mfma_f32_16x16x32_bf16 v[78:81], v[154:157], v[200:203], 0
	v_mfma_f32_16x16x32_bf16 v[74:77], v[162:165], v[200:203], 0
	v_mfma_f32_16x16x32_bf16 v[126:129], v[158:161], v[180:183], v[126:129]
	v_mfma_f32_16x16x32_bf16 v[122:125], v[166:169], v[180:183], v[122:125]
	v_mfma_f32_16x16x32_bf16 v[110:113], v[158:161], v[188:191], v[110:113]
	v_mfma_f32_16x16x32_bf16 v[106:109], v[166:169], v[188:191], v[106:109]
	v_mfma_f32_16x16x32_bf16 v[94:97], v[158:161], v[196:199], v[94:97]
	v_mfma_f32_16x16x32_bf16 v[90:93], v[166:169], v[196:199], v[90:93]
	v_mfma_f32_16x16x32_bf16 v[78:81], v[158:161], v[204:207], v[78:81]
	v_mfma_f32_16x16x32_bf16 v[74:77], v[166:169], v[204:207], v[74:77]
	v_mfma_f32_16x16x32_bf16 v[118:121], v[208:211], v[176:179], 0
	v_mfma_f32_16x16x32_bf16 v[114:117], v[216:219], v[176:179], 0
	v_mfma_f32_16x16x32_bf16 v[102:105], v[208:211], v[184:187], 0
	v_mfma_f32_16x16x32_bf16 v[98:101], v[216:219], v[184:187], 0
	v_mfma_f32_16x16x32_bf16 v[86:89], v[208:211], v[192:195], 0
	v_mfma_f32_16x16x32_bf16 v[82:85], v[216:219], v[192:195], 0
	v_mfma_f32_16x16x32_bf16 v[70:73], v[208:211], v[200:203], 0
	v_mfma_f32_16x16x32_bf16 v[66:69], v[216:219], v[200:203], 0
	v_mfma_f32_16x16x32_bf16 v[118:121], v[212:215], v[180:183], v[118:121]
	v_mfma_f32_16x16x32_bf16 v[114:117], v[220:223], v[180:183], v[114:117]
	v_mfma_f32_16x16x32_bf16 v[102:105], v[212:215], v[188:191], v[102:105]
	v_mfma_f32_16x16x32_bf16 v[98:101], v[220:223], v[188:191], v[98:101]
	v_mfma_f32_16x16x32_bf16 v[86:89], v[212:215], v[196:199], v[86:89]
	v_mfma_f32_16x16x32_bf16 v[82:85], v[220:223], v[196:199], v[82:85]
	v_mfma_f32_16x16x32_bf16 v[70:73], v[212:215], v[204:207], v[70:73]
	v_mfma_f32_16x16x32_bf16 v[66:69], v[220:223], v[204:207], v[66:69]
	s_barrier
	s_setprio 0
	s_add_i32 s20, s72, s52
	v_lshl_add_u64 v[172:173], s[34:35], 0, v[134:135]
	s_mov_b32 m0, s20
	s_nop 0
	global_load_lds_dwordx4 v[172:173], off
	v_lshl_add_u64 v[224:225], s[34:35], 0, v[130:131]
	s_add_i32 m0, s20, 0x2000
	s_nop 0
	global_load_lds_dwordx4 v[224:225], off
	s_mov_b32 m0, s53
	v_lshl_add_u64 v[226:227], s[18:19], 0, v[136:137]
	ds_read_b128 v[176:179], v152 offset:16384
	ds_read_b128 v[180:183], v152 offset:17408
	ds_read_b128 v[184:187], v152 offset:18432
	ds_read_b128 v[188:191], v152 offset:19456
	ds_read_b128 v[192:195], v152 offset:20480
	ds_read_b128 v[196:199], v152 offset:21504
	ds_read_b128 v[200:203], v152 offset:22528
	ds_read_b128 v[204:207], v152 offset:23552
	global_load_lds_dwordx4 v[226:227], off
	v_lshl_add_u64 v[228:229], s[18:19], 0, v[132:133]
	s_mov_b32 m0, s54
	s_nop 0
	global_load_lds_dwordx4 v[228:229], off
	s_waitcnt vmcnt(14)
	s_waitcnt lgkmcnt(0)
	s_setprio 1
	s_barrier
	v_mfma_f32_16x16x32_bf16 v[62:65], v[154:157], v[176:179], 0
	v_mfma_f32_16x16x32_bf16 v[58:61], v[162:165], v[176:179], 0
	v_mfma_f32_16x16x32_bf16 v[46:49], v[154:157], v[184:187], 0
	v_mfma_f32_16x16x32_bf16 v[42:45], v[162:165], v[184:187], 0
	v_mfma_f32_16x16x32_bf16 v[30:33], v[154:157], v[192:195], 0
	v_mfma_f32_16x16x32_bf16 v[26:29], v[162:165], v[192:195], 0
	v_mfma_f32_16x16x32_bf16 v[14:17], v[154:157], v[200:203], 0
	v_mfma_f32_16x16x32_bf16 v[10:13], v[162:165], v[200:203], 0
	v_mfma_f32_16x16x32_bf16 v[62:65], v[158:161], v[180:183], v[62:65]
	v_mfma_f32_16x16x32_bf16 v[58:61], v[166:169], v[180:183], v[58:61]
	v_mfma_f32_16x16x32_bf16 v[46:49], v[158:161], v[188:191], v[46:49]
	v_mfma_f32_16x16x32_bf16 v[42:45], v[166:169], v[188:191], v[42:45]
	v_mfma_f32_16x16x32_bf16 v[30:33], v[158:161], v[196:199], v[30:33]
	v_mfma_f32_16x16x32_bf16 v[26:29], v[166:169], v[196:199], v[26:29]
	v_mfma_f32_16x16x32_bf16 v[14:17], v[158:161], v[204:207], v[14:17]
	v_mfma_f32_16x16x32_bf16 v[10:13], v[166:169], v[204:207], v[10:13]
	v_mfma_f32_16x16x32_bf16 v[54:57], v[208:211], v[176:179], 0
	v_mfma_f32_16x16x32_bf16 v[50:53], v[216:219], v[176:179], 0
	v_mfma_f32_16x16x32_bf16 v[38:41], v[208:211], v[184:187], 0
	v_mfma_f32_16x16x32_bf16 v[34:37], v[216:219], v[184:187], 0
	v_mfma_f32_16x16x32_bf16 v[22:25], v[208:211], v[192:195], 0
	v_mfma_f32_16x16x32_bf16 v[18:21], v[216:219], v[192:195], 0
	v_mfma_f32_16x16x32_bf16 v[6:9], v[208:211], v[200:203], 0
	v_mfma_f32_16x16x32_bf16 v[2:5], v[216:219], v[200:203], 0
	v_mfma_f32_16x16x32_bf16 v[54:57], v[212:215], v[180:183], v[54:57]
	v_mfma_f32_16x16x32_bf16 v[50:53], v[220:223], v[180:183], v[50:53]
	v_mfma_f32_16x16x32_bf16 v[38:41], v[212:215], v[188:191], v[38:41]
	v_mfma_f32_16x16x32_bf16 v[34:37], v[220:223], v[188:191], v[34:37]
	v_mfma_f32_16x16x32_bf16 v[22:25], v[212:215], v[196:199], v[22:25]
	v_mfma_f32_16x16x32_bf16 v[18:21], v[220:223], v[196:199], v[18:21]
	v_mfma_f32_16x16x32_bf16 v[6:9], v[212:215], v[204:207], v[6:9]
	v_mfma_f32_16x16x32_bf16 v[2:5], v[220:223], v[204:207], v[2:5]
	s_barrier
	s_setprio 0
	s_add_u32 s20, s34, 0x40000
	s_addc_u32 s21, s35, 0
	s_add_i32 s60, s73, s52
	v_lshl_add_u64 v[246:247], s[20:21], 0, v[134:135]
	s_mov_b32 m0, s60
	s_nop 0
	global_load_lds_dwordx4 v[246:247], off
	v_lshl_add_u64 v[246:247], s[20:21], 0, v[130:131]
	s_add_i32 m0, s60, 0x2000
	s_nop 0
	global_load_lds_dwordx4 v[246:247], off
	s_add_i32 s20, 0, 0x18000
	v_add_u32_e32 v166, s20, v150
	ds_read_b128 v[154:157], v166
	ds_read_b128 v[158:161], v166 offset:1024
	ds_read_b128 v[162:165], v166 offset:2048
	ds_read_b128 v[166:169], v166 offset:3072
	s_add_u32 s18, s18, 0x40000
	s_addc_u32 s19, s19, 0
	s_mov_b32 m0, s55
	v_lshl_add_u64 v[208:209], s[18:19], 0, v[136:137]
	ds_read_b128 v[176:179], v152 offset:32768
	ds_read_b128 v[180:183], v152 offset:33792
	ds_read_b128 v[184:187], v152 offset:34816
	ds_read_b128 v[188:191], v152 offset:35840
	ds_read_b128 v[192:195], v152 offset:36864
	ds_read_b128 v[196:199], v152 offset:37888
	ds_read_b128 v[200:203], v152 offset:38912
	ds_read_b128 v[204:207], v152 offset:39936
	global_load_lds_dwordx4 v[208:209], off
	v_lshl_add_u64 v[208:209], s[18:19], 0, v[132:133]
	s_mov_b32 m0, s56
	s_nop 0
	global_load_lds_dwordx4 v[208:209], off
	s_add_i32 s21, 0, 0x1c000
	v_add_u32_e32 v171, s21, v150
	ds_read_b128 v[208:211], v171
	ds_read_b128 v[212:215], v171 offset:1024
	ds_read_b128 v[216:219], v171 offset:2048
	ds_read_b128 v[220:223], v171 offset:3072
	s_waitcnt vmcnt(8)
	s_waitcnt lgkmcnt(0)
	s_setprio 1
	s_barrier
	v_mfma_f32_16x16x32_bf16 v[126:129], v[154:157], v[176:179], v[126:129]
	v_mfma_f32_16x16x32_bf16 v[122:125], v[162:165], v[176:179], v[122:125]
	v_mfma_f32_16x16x32_bf16 v[110:113], v[154:157], v[184:187], v[110:113]
	v_mfma_f32_16x16x32_bf16 v[106:109], v[162:165], v[184:187], v[106:109]
	v_mfma_f32_16x16x32_bf16 v[94:97], v[154:157], v[192:195], v[94:97]
	v_mfma_f32_16x16x32_bf16 v[90:93], v[162:165], v[192:195], v[90:93]
	v_mfma_f32_16x16x32_bf16 v[78:81], v[154:157], v[200:203], v[78:81]
	v_mfma_f32_16x16x32_bf16 v[74:77], v[162:165], v[200:203], v[74:77]
	v_mfma_f32_16x16x32_bf16 v[126:129], v[158:161], v[180:183], v[126:129]
	v_mfma_f32_16x16x32_bf16 v[122:125], v[166:169], v[180:183], v[122:125]
	v_mfma_f32_16x16x32_bf16 v[110:113], v[158:161], v[188:191], v[110:113]
	v_mfma_f32_16x16x32_bf16 v[106:109], v[166:169], v[188:191], v[106:109]
	v_mfma_f32_16x16x32_bf16 v[94:97], v[158:161], v[196:199], v[94:97]
	v_mfma_f32_16x16x32_bf16 v[90:93], v[166:169], v[196:199], v[90:93]
	v_mfma_f32_16x16x32_bf16 v[78:81], v[158:161], v[204:207], v[78:81]
	v_mfma_f32_16x16x32_bf16 v[74:77], v[166:169], v[204:207], v[74:77]
	v_mfma_f32_16x16x32_bf16 v[118:121], v[208:211], v[176:179], v[118:121]
	v_mfma_f32_16x16x32_bf16 v[114:117], v[216:219], v[176:179], v[114:117]
	v_mfma_f32_16x16x32_bf16 v[102:105], v[208:211], v[184:187], v[102:105]
	v_mfma_f32_16x16x32_bf16 v[98:101], v[216:219], v[184:187], v[98:101]
	v_mfma_f32_16x16x32_bf16 v[86:89], v[208:211], v[192:195], v[86:89]
	v_mfma_f32_16x16x32_bf16 v[82:85], v[216:219], v[192:195], v[82:85]
	v_mfma_f32_16x16x32_bf16 v[70:73], v[208:211], v[200:203], v[70:73]
	v_mfma_f32_16x16x32_bf16 v[66:69], v[216:219], v[200:203], v[66:69]
	v_mfma_f32_16x16x32_bf16 v[118:121], v[212:215], v[180:183], v[118:121]
	v_mfma_f32_16x16x32_bf16 v[114:117], v[220:223], v[180:183], v[114:117]
	v_mfma_f32_16x16x32_bf16 v[102:105], v[212:215], v[188:191], v[102:105]
	v_mfma_f32_16x16x32_bf16 v[98:101], v[220:223], v[188:191], v[98:101]
	v_mfma_f32_16x16x32_bf16 v[86:89], v[212:215], v[196:199], v[86:89]
	v_mfma_f32_16x16x32_bf16 v[82:85], v[220:223], v[196:199], v[82:85]
	v_mfma_f32_16x16x32_bf16 v[70:73], v[212:215], v[204:207], v[70:73]
	v_mfma_f32_16x16x32_bf16 v[66:69], v[220:223], v[204:207], v[66:69]
	s_barrier
	s_setprio 0
	s_add_i32 s18, s20, s52
	v_lshl_add_u64 v[172:173], v[172:173], 0, s[4:5]
	s_mov_b32 m0, s18
	s_nop 0
	global_load_lds_dwordx4 v[172:173], off
	v_lshl_add_u64 v[172:173], v[224:225], 0, s[4:5]
	s_add_i32 m0, s18, 0x2000
	s_nop 0
	global_load_lds_dwordx4 v[172:173], off
	s_mov_b32 m0, s68
	v_lshl_add_u64 v[172:173], v[226:227], 0, s[4:5]
	ds_read_b128 v[176:179], v152 offset:49152
	ds_read_b128 v[180:183], v152 offset:50176
	ds_read_b128 v[184:187], v152 offset:51200
	ds_read_b128 v[188:191], v152 offset:52224
	ds_read_b128 v[192:195], v152 offset:53248
	ds_read_b128 v[196:199], v152 offset:54272
	ds_read_b128 v[200:203], v152 offset:55296
	ds_read_b128 v[204:207], v152 offset:56320
	global_load_lds_dwordx4 v[172:173], off
	v_lshl_add_u64 v[172:173], v[228:229], 0, s[4:5]
	s_mov_b32 m0, s69
	s_nop 0
	global_load_lds_dwordx4 v[172:173], off
	s_add_u32 s18, s34, 0x40080
	s_addc_u32 s19, s35, 0
	s_add_i32 s20, s21, s52
	v_lshl_add_u64 v[248:249], s[18:19], 0, v[134:135]
	s_mov_b32 m0, s20
	s_nop 0
	global_load_lds_dwordx4 v[248:249], off
	v_lshl_add_u64 v[248:249], s[18:19], 0, v[130:131]
	s_add_i32 m0, s20, 0x2000
	s_nop 0
	global_load_lds_dwordx4 v[248:249], off
	s_waitcnt vmcnt(6)
	s_waitcnt lgkmcnt(0)
	s_setprio 1
	s_barrier
	v_mfma_f32_16x16x32_bf16 v[62:65], v[154:157], v[176:179], v[62:65]
	v_mfma_f32_16x16x32_bf16 v[58:61], v[162:165], v[176:179], v[58:61]
	v_mfma_f32_16x16x32_bf16 v[46:49], v[154:157], v[184:187], v[46:49]
	v_mfma_f32_16x16x32_bf16 v[42:45], v[162:165], v[184:187], v[42:45]
	v_mfma_f32_16x16x32_bf16 v[30:33], v[154:157], v[192:195], v[30:33]
	v_mfma_f32_16x16x32_bf16 v[26:29], v[162:165], v[192:195], v[26:29]
	v_mfma_f32_16x16x32_bf16 v[14:17], v[154:157], v[200:203], v[14:17]
	v_mfma_f32_16x16x32_bf16 v[10:13], v[162:165], v[200:203], v[10:13]
	v_mfma_f32_16x16x32_bf16 v[62:65], v[158:161], v[180:183], v[62:65]
	v_mfma_f32_16x16x32_bf16 v[58:61], v[166:169], v[180:183], v[58:61]
	v_mfma_f32_16x16x32_bf16 v[46:49], v[158:161], v[188:191], v[46:49]
	v_mfma_f32_16x16x32_bf16 v[42:45], v[166:169], v[188:191], v[42:45]
	v_mfma_f32_16x16x32_bf16 v[30:33], v[158:161], v[196:199], v[30:33]
	v_mfma_f32_16x16x32_bf16 v[26:29], v[166:169], v[196:199], v[26:29]
	v_mfma_f32_16x16x32_bf16 v[14:17], v[158:161], v[204:207], v[14:17]
	v_mfma_f32_16x16x32_bf16 v[10:13], v[166:169], v[204:207], v[10:13]
	v_mfma_f32_16x16x32_bf16 v[54:57], v[208:211], v[176:179], v[54:57]
	v_mfma_f32_16x16x32_bf16 v[50:53], v[216:219], v[176:179], v[50:53]
	v_mfma_f32_16x16x32_bf16 v[38:41], v[208:211], v[184:187], v[38:41]
	v_mfma_f32_16x16x32_bf16 v[34:37], v[216:219], v[184:187], v[34:37]
	v_mfma_f32_16x16x32_bf16 v[22:25], v[208:211], v[192:195], v[22:25]
	v_mfma_f32_16x16x32_bf16 v[18:21], v[216:219], v[192:195], v[18:21]
	v_mfma_f32_16x16x32_bf16 v[6:9], v[208:211], v[200:203], v[6:9]
	v_mfma_f32_16x16x32_bf16 v[2:5], v[216:219], v[200:203], v[2:5]
	v_mfma_f32_16x16x32_bf16 v[54:57], v[212:215], v[180:183], v[54:57]
	v_mfma_f32_16x16x32_bf16 v[50:53], v[220:223], v[180:183], v[50:53]
	v_mfma_f32_16x16x32_bf16 v[38:41], v[212:215], v[188:191], v[38:41]
	v_mfma_f32_16x16x32_bf16 v[34:37], v[220:223], v[188:191], v[34:37]
	v_mfma_f32_16x16x32_bf16 v[22:25], v[212:215], v[196:199], v[22:25]
	v_mfma_f32_16x16x32_bf16 v[18:21], v[220:223], v[196:199], v[18:21]
	v_mfma_f32_16x16x32_bf16 v[6:9], v[212:215], v[204:207], v[6:9]
	v_mfma_f32_16x16x32_bf16 v[2:5], v[220:223], v[204:207], v[2:5]
	s_add_i32 s79, s79, 2
	s_add_u32 s16, s16, 0x100
	s_addc_u32 s17, s17, 0
	s_add_u32 s77, s77, 0x100
	s_addc_u32 s78, s78, 0
	s_cmp_gt_u32 s79, 13

.LBB0_1367:
	s_add_u32 s0, s30, 0x1a2d800
	s_addc_u32 s1, s31, 0
	s_add_u32 s77, s30, 0xa9000
	s_addc_u32 s78, s31, 0
	s_add_u32 s6, s30, 0x19c800
	s_addc_u32 s7, s31, 0
	s_add_u32 s8, s30, 0x9b00000
	s_addc_u32 s9, s31, 0
	s_add_u32 s10, s30, 0x10700000
	s_addc_u32 s11, s31, 0
	s_add_u32 s12, s30, 0x12700000
	s_addc_u32 s13, s31, 0
	s_add_u32 s14, s30, 0x14700000
	s_addc_u32 s15, s31, 0
	s_add_u32 s16, s30, 0x1b00000
	s_addc_u32 s17, s31, 0
	s_add_u32 s79, s30, 0xbf00000
	s_addc_u32 s87, s31, 0
	s_add_u32 s89, s30, 0xe300000
	s_mov_b64 s[24:25], 0x80
	s_addc_u32 s92, s31, 0
	s_and_b32 s3, s19, 3
	s_add_i32 m0, s72, 0x18000
	v_lshl_add_u64 v[8:9], v[8:9], 0, s[24:25]
	s_ashr_i32 s93, s22, 31
	s_lshl_b32 s94, s18, 6
	s_lshl_b32 s5, s18, 13
	s_lshl_b32 s20, s3, 12
	s_waitcnt vmcnt(0)
	s_barrier
	global_load_lds_dwordx4 v[8:9], off
	v_lshl_add_u64 v[6:7], v[6:7], 0, s[24:25]
	s_add_i32 m0, s72, 0x1a000
	s_add_i32 s95, s72, 0x8000
	s_add_i32 s96, s72, 0xa000
	global_load_lds_dwordx4 v[6:7], off
	v_lshl_add_u64 v[4:5], v[4:5], 0, s[24:25]
	s_mov_b32 m0, s95
	s_add_u32 s18, s54, 0x40080
	global_load_lds_dwordx4 v[4:5], off
	v_lshl_add_u64 v[2:3], v[2:3], 0, s[24:25]
	s_mov_b32 m0, s96
	s_addc_u32 s19, s55, 0
	global_load_lds_dwordx4 v[2:3], off
	s_add_i32 m0, s72, 0x1c000
	v_lshl_add_u64 v[2:3], s[18:19], 0, v[164:165]
	global_load_lds_dwordx4 v[2:3], off
	v_lshl_add_u64 v[2:3], s[18:19], 0, v[168:169]
	s_add_i32 m0, s72, 0x1e000
	v_lshlrev_b32_e32 v4, 6, v170
	global_load_lds_dwordx4 v[2:3], off
	v_bfe_u32 v2, v170, 4, 2
	v_lshlrev_b32_e32 v3, 3, v2
	v_lshlrev_b32_e32 v2, 4, v2
	s_movk_i32 s18, 0x3c0
	v_lshlrev_b32_e32 v5, 2, v170
	v_and_or_b32 v4, v4, s18, v2
	v_and_b32_e32 v5, 32, v5
	v_lshl_or_b32 v224, s3, 5, v3
	v_lshlrev_b32_e32 v3, 8, v170
	v_bitop3_b32 v175, s20, v4, v5 bitop3:0xf6
	v_and_b32_e32 v3, 0x38000, v3
	v_lshlrev_b32_e32 v4, 11, v12
	v_or3_b32 v3, v10, v3, v4
	v_lshlrev_b32_e32 v6, 2, v171
	v_add_u32_e32 v178, v3, v11
	v_lshlrev_b32_e32 v3, 4, v13
	v_lshl_or_b32 v2, v171, 6, v2
	v_and_b32_e32 v6, 32, v6
	s_waitcnt vmcnt(6)
	v_and_b32_e32 v3, 0x78000, v3
	v_bitop3_b32 v2, v2, s5, v6 bitop3:0xde
	v_or3_b32 v3, v10, v3, v4
	s_add_i32 s33, 0, 0x10000
	s_add_i32 s64, 0, 0x14000
	s_mov_b32 s97, s22
	v_mov_b32_e32 v179, v177
	v_add_u32_e32 v180, v3, v11
	v_mov_b32_e32 v181, v177
	v_mov_b64_e32 v[182:183], 0xbff
	v_add_u32_e32 v225, s33, v175
	v_add_u32_e32 v226, 0, v2
	v_add_u32_e32 v227, s64, v175
	v_mov_b64_e32 v[184:185], 0x5f
	v_mov_b32_e32 v228, 0x80
	s_barrier
	global_load_dword v255, v[8:9], off
	global_load_dword v255, v[8:9], off
	global_load_dword v255, v[8:9], off
	global_load_dword v255, v[8:9], off
	global_load_dword v255, v[8:9], off
	global_load_dword v255, v[8:9], off
	global_load_dword v255, v[8:9], off
	global_load_dword v255, v[8:9], off
	global_load_dword v255, v[8:9], off
	global_load_dword v255, v[8:9], off
	global_load_dword v255, v[8:9], off
	global_load_dword v255, v[8:9], off
	global_load_dword v255, v[8:9], off
	global_load_dword v255, v[8:9], off
	global_load_dword v255, v[8:9], off
	global_load_dword v255, v[8:9], off
	s_branch .LBB0_1369

.LBB0_1374:
	s_ashr_i32 s41, s40, 31
	s_xor_b64 s[50:51], s[18:19], -1
	s_lshl_b64 s[20:21], s[40:41], 19
	s_add_u32 s48, s65, s20
	s_addc_u32 s49, s66, s21
	s_and_b64 s[20:21], s[18:19], exec
	s_cselect_b32 s3, s49, s35
	s_cselect_b32 s5, s48, s34
	s_ashr_i32 s39, s38, 31
	s_lshl_b64 s[20:21], s[38:39], 19
	s_add_u32 s52, s67, s20
	s_addc_u32 s53, s68, s21
	s_and_b64 s[18:19], s[18:19], exec
	s_cselect_b32 s39, s53, s55
	s_cselect_b32 s41, s52, s54
	s_add_u32 s34, s34, 0x40080
	s_addc_u32 s35, s35, 0
	s_add_u32 s56, s54, 0x100
	s_addc_u32 s57, s55, 0
	s_mov_b32 vcc_lo, -2
	s_waitcnt vmcnt(0)
	ds_read_b128 v[10:13], v225
	ds_read_b128 v[14:17], v225 offset:1024
	ds_read_b128 v[26:29], v225 offset:2048
	ds_read_b128 v[30:33], v225 offset:3072
	s_add_u32 s18, s34, 0xfffc0080
	s_addc_u32 s19, s35, -1
	s_cmp_eq_u32 vcc_lo, 12
	s_cselect_b32 s19, s3, s19
	s_cselect_b32 s18, s5, s18
	s_cselect_b32 s55, s39, s57
	s_cselect_b32 s54, s41, s56
	v_lshl_add_u64 v[202:203], s[34:35], 0, v[178:179]
	s_add_i32 m0, s72, 0xc000
	ds_read_b128 v[34:37], v226
	ds_read_b128 v[38:41], v226 offset:1024
	ds_read_b128 v[50:53], v226 offset:2048
	ds_read_b128 v[54:57], v226 offset:3072
	ds_read_b128 v[186:189], v226 offset:4096
	ds_read_b128 v[190:193], v226 offset:5120
	ds_read_b128 v[194:197], v226 offset:6144
	ds_read_b128 v[198:201], v226 offset:7168
	global_load_lds_dwordx4 v[202:203], off
	v_lshl_add_u64 v[202:203], s[34:35], 0, v[180:181]
	s_add_i32 m0, s72, 0xe000
	s_nop 0
	global_load_lds_dwordx4 v[202:203], off
	ds_read_b128 v[202:205], v227
	ds_read_b128 v[206:209], v227 offset:1024
	ds_read_b128 v[210:213], v227 offset:2048
	ds_read_b128 v[214:217], v227 offset:3072
	s_waitcnt lgkmcnt(0)
	s_setprio 1
	s_barrier
	v_mfma_f32_16x16x32_bf16 v[158:161], v[10:13], v[34:37], 0
	v_mfma_f32_16x16x32_bf16 v[154:157], v[26:29], v[34:37], 0
	v_mfma_f32_16x16x32_bf16 v[142:145], v[10:13], v[50:53], 0
	v_mfma_f32_16x16x32_bf16 v[138:141], v[26:29], v[50:53], 0
	v_mfma_f32_16x16x32_bf16 v[126:129], v[10:13], v[186:189], 0
	v_mfma_f32_16x16x32_bf16 v[122:125], v[26:29], v[186:189], 0
	v_mfma_f32_16x16x32_bf16 v[110:113], v[10:13], v[194:197], 0
	v_mfma_f32_16x16x32_bf16 v[106:109], v[26:29], v[194:197], 0
	v_mfma_f32_16x16x32_bf16 v[158:161], v[14:17], v[38:41], v[158:161]
	v_mfma_f32_16x16x32_bf16 v[154:157], v[30:33], v[38:41], v[154:157]
	v_mfma_f32_16x16x32_bf16 v[142:145], v[14:17], v[54:57], v[142:145]
	v_mfma_f32_16x16x32_bf16 v[138:141], v[30:33], v[54:57], v[138:141]
	v_mfma_f32_16x16x32_bf16 v[126:129], v[14:17], v[190:193], v[126:129]
	v_mfma_f32_16x16x32_bf16 v[122:125], v[30:33], v[190:193], v[122:125]
	v_mfma_f32_16x16x32_bf16 v[110:113], v[14:17], v[198:201], v[110:113]
	v_mfma_f32_16x16x32_bf16 v[106:109], v[30:33], v[198:201], v[106:109]
	v_mfma_f32_16x16x32_bf16 v[150:153], v[202:205], v[34:37], 0
	v_mfma_f32_16x16x32_bf16 v[34:37], v[210:213], v[34:37], 0
	v_mfma_f32_16x16x32_bf16 v[150:153], v[206:209], v[38:41], v[150:153]
	v_mfma_f32_16x16x32_bf16 v[34:37], v[214:217], v[38:41], v[34:37]
	v_mfma_f32_16x16x32_bf16 v[38:41], v[202:205], v[50:53], 0
	v_mfma_f32_16x16x32_bf16 v[50:53], v[210:213], v[50:53], 0
	v_mfma_f32_16x16x32_bf16 v[114:117], v[210:213], v[186:189], 0
	v_mfma_f32_16x16x32_bf16 v[102:105], v[202:205], v[194:197], 0
	v_mfma_f32_16x16x32_bf16 v[98:101], v[210:213], v[194:197], 0
	v_mfma_f32_16x16x32_bf16 v[38:41], v[206:209], v[54:57], v[38:41]
	v_mfma_f32_16x16x32_bf16 v[50:53], v[214:217], v[54:57], v[50:53]
	v_mfma_f32_16x16x32_bf16 v[54:57], v[202:205], v[186:189], 0
	v_mfma_f32_16x16x32_bf16 v[114:117], v[214:217], v[190:193], v[114:117]
	v_mfma_f32_16x16x32_bf16 v[102:105], v[206:209], v[198:201], v[102:105]
	v_mfma_f32_16x16x32_bf16 v[98:101], v[214:217], v[198:201], v[98:101]
	v_mfma_f32_16x16x32_bf16 v[54:57], v[206:209], v[190:193], v[54:57]
	s_barrier
	s_setprio 0
	s_add_i32 s20, s33, s71
	v_lshl_add_u64 v[222:223], s[54:55], 0, v[164:165]
	s_mov_b32 m0, s20
	s_nop 0
	global_load_lds_dwordx4 v[222:223], off
	v_lshl_add_u64 v[238:239], s[54:55], 0, v[168:169]
	s_add_i32 m0, s20, 0x2000
	s_nop 0
	global_load_lds_dwordx4 v[238:239], off
	s_mov_b32 m0, s72
	v_lshl_add_u64 v[240:241], s[18:19], 0, v[162:163]
	ds_read_b128 v[118:121], v226 offset:16384
	ds_read_b128 v[130:133], v226 offset:17408
	ds_read_b128 v[134:137], v226 offset:18432
	ds_read_b128 v[146:149], v226 offset:19456
	ds_read_b128 v[186:189], v226 offset:20480
	ds_read_b128 v[190:193], v226 offset:21504
	ds_read_b128 v[194:197], v226 offset:22528
	ds_read_b128 v[198:201], v226 offset:23552
	global_load_lds_dwordx4 v[240:241], off
	v_lshl_add_u64 v[242:243], s[18:19], 0, v[166:167]
	s_mov_b32 m0, s73
	s_nop 0
	global_load_lds_dwordx4 v[242:243], off
	s_waitcnt vmcnt(22)
	s_waitcnt lgkmcnt(0)
	s_setprio 1
	s_barrier
	v_mfma_f32_16x16x32_bf16 v[94:97], v[10:13], v[118:121], 0
	v_mfma_f32_16x16x32_bf16 v[90:93], v[26:29], v[118:121], 0
	v_mfma_f32_16x16x32_bf16 v[78:81], v[10:13], v[134:137], 0
	v_mfma_f32_16x16x32_bf16 v[74:77], v[26:29], v[134:137], 0
	v_mfma_f32_16x16x32_bf16 v[62:65], v[10:13], v[186:189], 0
	v_mfma_f32_16x16x32_bf16 v[58:61], v[26:29], v[186:189], 0
	v_mfma_f32_16x16x32_bf16 v[10:13], v[10:13], v[194:197], 0
	v_mfma_f32_16x16x32_bf16 v[94:97], v[14:17], v[130:133], v[94:97]
	v_mfma_f32_16x16x32_bf16 v[90:93], v[30:33], v[130:133], v[90:93]
	v_mfma_f32_16x16x32_bf16 v[78:81], v[14:17], v[146:149], v[78:81]
	v_mfma_f32_16x16x32_bf16 v[74:77], v[30:33], v[146:149], v[74:77]
	v_mfma_f32_16x16x32_bf16 v[62:65], v[14:17], v[190:193], v[62:65]
	v_mfma_f32_16x16x32_bf16 v[58:61], v[30:33], v[190:193], v[58:61]
	v_mfma_f32_16x16x32_bf16 v[10:13], v[14:17], v[198:201], v[10:13]
	v_mfma_f32_16x16x32_bf16 v[14:17], v[26:29], v[194:197], 0
	v_mfma_f32_16x16x32_bf16 v[14:17], v[30:33], v[198:201], v[14:17]
	v_mfma_f32_16x16x32_bf16 v[18:21], v[202:205], v[118:121], 0
	v_mfma_f32_16x16x32_bf16 v[26:29], v[206:209], v[130:133], v[18:21]
	v_mfma_f32_16x16x32_bf16 v[18:21], v[210:213], v[118:121], 0
	v_mfma_f32_16x16x32_bf16 v[30:33], v[214:217], v[130:133], v[18:21]
	v_mfma_f32_16x16x32_bf16 v[18:21], v[202:205], v[134:137], 0
	v_mfma_f32_16x16x32_bf16 v[70:73], v[206:209], v[146:149], v[18:21]
	v_mfma_f32_16x16x32_bf16 v[18:21], v[210:213], v[134:137], 0
	v_mfma_f32_16x16x32_bf16 v[66:69], v[214:217], v[146:149], v[18:21]
	v_mfma_f32_16x16x32_bf16 v[18:21], v[202:205], v[186:189], 0
	v_mfma_f32_16x16x32_bf16 v[46:49], v[206:209], v[190:193], v[18:21]
	v_mfma_f32_16x16x32_bf16 v[18:21], v[210:213], v[186:189], 0
	v_mfma_f32_16x16x32_bf16 v[6:9], v[202:205], v[194:197], 0
	v_mfma_f32_16x16x32_bf16 v[2:5], v[210:213], v[194:197], 0
	v_mfma_f32_16x16x32_bf16 v[42:45], v[214:217], v[190:193], v[18:21]
	v_mfma_f32_16x16x32_bf16 v[6:9], v[206:209], v[198:201], v[6:9]
	v_mfma_f32_16x16x32_bf16 v[2:5], v[214:217], v[198:201], v[2:5]
	s_barrier
	s_setprio 0
	s_add_u32 s20, s54, 0x40000
	s_addc_u32 s21, s55, 0
	s_add_i32 s60, s64, s71
	v_lshl_add_u64 v[246:247], s[20:21], 0, v[164:165]
	s_mov_b32 m0, s60
	s_nop 0
	global_load_lds_dwordx4 v[246:247], off
	v_lshl_add_u64 v[246:247], s[20:21], 0, v[168:169]
	s_add_i32 m0, s60, 0x2000
	s_nop 0
	global_load_lds_dwordx4 v[246:247], off
	s_add_i32 s20, 0, 0x18000
	v_add_u32_e32 v86, s20, v175
	ds_read_b128 v[18:21], v86
	ds_read_b128 v[22:25], v86 offset:1024
	ds_read_b128 v[82:85], v86 offset:2048
	ds_read_b128 v[86:89], v86 offset:3072
	s_add_u32 s18, s18, 0x40000
	s_addc_u32 s19, s19, 0
	s_mov_b32 m0, s74
	v_lshl_add_u64 v[134:135], s[18:19], 0, v[162:163]
	ds_read_b128 v[118:121], v226 offset:32768
	ds_read_b128 v[130:133], v226 offset:33792
	ds_read_b128 v[186:189], v226 offset:34816
	ds_read_b128 v[190:193], v226 offset:35840
	ds_read_b128 v[194:197], v226 offset:36864
	ds_read_b128 v[198:201], v226 offset:37888
	ds_read_b128 v[202:205], v226 offset:38912
	ds_read_b128 v[206:209], v226 offset:39936
	global_load_lds_dwordx4 v[134:135], off
	v_lshl_add_u64 v[134:135], s[18:19], 0, v[166:167]
	s_mov_b32 m0, s75
	s_nop 0
	global_load_lds_dwordx4 v[134:135], off
	s_add_i32 s21, 0, 0x1c000
	v_add_u32_e32 v244, s21, v175
	ds_read_b128 v[210:213], v244
	ds_read_b128 v[214:217], v244 offset:1024
	ds_read_b128 v[218:221], v244 offset:2048
	ds_read_b128 v[234:237], v244 offset:3072
	s_waitcnt vmcnt(8)
	s_waitcnt lgkmcnt(0)
	s_setprio 1
	s_barrier
	v_mfma_f32_16x16x32_bf16 v[134:137], v[18:21], v[118:121], v[158:161]
	v_mfma_f32_16x16x32_bf16 v[158:161], v[22:25], v[130:133], v[134:137]
	v_mfma_f32_16x16x32_bf16 v[134:137], v[82:85], v[118:121], v[154:157]
	v_mfma_f32_16x16x32_bf16 v[154:157], v[86:89], v[130:133], v[134:137]
	v_mfma_f32_16x16x32_bf16 v[134:137], v[18:21], v[186:189], v[142:145]
	v_mfma_f32_16x16x32_bf16 v[142:145], v[22:25], v[190:193], v[134:137]
	v_mfma_f32_16x16x32_bf16 v[134:137], v[82:85], v[186:189], v[138:141]
	v_mfma_f32_16x16x32_bf16 v[126:129], v[18:21], v[194:197], v[126:129]
	v_mfma_f32_16x16x32_bf16 v[122:125], v[82:85], v[194:197], v[122:125]
	v_mfma_f32_16x16x32_bf16 v[110:113], v[18:21], v[202:205], v[110:113]
	v_mfma_f32_16x16x32_bf16 v[106:109], v[82:85], v[202:205], v[106:109]
	v_mfma_f32_16x16x32_bf16 v[138:141], v[86:89], v[190:193], v[134:137]
	v_mfma_f32_16x16x32_bf16 v[126:129], v[22:25], v[198:201], v[126:129]
	v_mfma_f32_16x16x32_bf16 v[122:125], v[86:89], v[198:201], v[122:125]
	v_mfma_f32_16x16x32_bf16 v[110:113], v[22:25], v[206:209], v[110:113]
	v_mfma_f32_16x16x32_bf16 v[106:109], v[86:89], v[206:209], v[106:109]
	v_mfma_f32_16x16x32_bf16 v[34:37], v[218:221], v[118:121], v[34:37]
	v_mfma_f32_16x16x32_bf16 v[134:137], v[210:213], v[118:121], v[150:153]
	v_mfma_f32_16x16x32_bf16 v[146:149], v[234:237], v[130:133], v[34:37]
	v_mfma_f32_16x16x32_bf16 v[34:37], v[210:213], v[186:189], v[38:41]
	v_mfma_f32_16x16x32_bf16 v[150:153], v[214:217], v[130:133], v[134:137]
	v_mfma_f32_16x16x32_bf16 v[134:137], v[214:217], v[190:193], v[34:37]
	v_mfma_f32_16x16x32_bf16 v[34:37], v[218:221], v[186:189], v[50:53]
	v_mfma_f32_16x16x32_bf16 v[130:133], v[234:237], v[190:193], v[34:37]
	v_mfma_f32_16x16x32_bf16 v[34:37], v[210:213], v[194:197], v[54:57]
	v_mfma_f32_16x16x32_bf16 v[118:121], v[214:217], v[198:201], v[34:37]
	v_mfma_f32_16x16x32_bf16 v[34:37], v[218:221], v[194:197], v[114:117]
	v_mfma_f32_16x16x32_bf16 v[114:117], v[234:237], v[198:201], v[34:37]
	v_mfma_f32_16x16x32_bf16 v[34:37], v[210:213], v[202:205], v[102:105]
	v_mfma_f32_16x16x32_bf16 v[102:105], v[214:217], v[206:209], v[34:37]
	v_mfma_f32_16x16x32_bf16 v[34:37], v[218:221], v[202:205], v[98:101]
	v_mfma_f32_16x16x32_bf16 v[98:101], v[234:237], v[206:209], v[34:37]
	s_barrier
	s_setprio 0
	s_add_i32 s18, s20, s71
	v_lshl_add_u64 v[248:249], v[222:223], 0, s[24:25]
	s_mov_b32 m0, s18
	s_nop 0
	global_load_lds_dwordx4 v[248:249], off
	v_lshl_add_u64 v[248:249], v[238:239], 0, s[24:25]
	s_add_i32 m0, s18, 0x2000
	s_nop 0
	global_load_lds_dwordx4 v[248:249], off
	s_mov_b32 m0, s95
	v_lshl_add_u64 v[202:203], v[240:241], 0, s[24:25]
	s_nop 2
	ds_read_b128 v[34:37], v226 offset:49152
	ds_read_b128 v[38:41], v226 offset:50176
	ds_read_b128 v[50:53], v226 offset:51200
	ds_read_b128 v[54:57], v226 offset:52224
	ds_read_b128 v[186:189], v226 offset:53248
	ds_read_b128 v[190:193], v226 offset:54272
	ds_read_b128 v[194:197], v226 offset:55296
	ds_read_b128 v[198:201], v226 offset:56320
	global_load_lds_dwordx4 v[202:203], off
	v_lshl_add_u64 v[202:203], v[242:243], 0, s[24:25]
	s_mov_b32 m0, s96
	s_nop 0
	global_load_lds_dwordx4 v[202:203], off
	s_add_u32 s18, s54, 0x40080
	s_addc_u32 s19, s55, 0
	s_add_i32 s20, s21, s71
	v_lshl_add_u64 v[250:251], s[18:19], 0, v[164:165]
	s_mov_b32 m0, s20
	s_nop 0
	global_load_lds_dwordx4 v[250:251], off
	v_lshl_add_u64 v[250:251], s[18:19], 0, v[168:169]
	s_add_i32 m0, s20, 0x2000
	s_nop 0
	global_load_lds_dwordx4 v[250:251], off
	s_waitcnt vmcnt(6)
	s_waitcnt lgkmcnt(0)
	s_setprio 1
	s_barrier
	v_mfma_f32_16x16x32_bf16 v[94:97], v[18:21], v[34:37], v[94:97]
	v_mfma_f32_16x16x32_bf16 v[78:81], v[18:21], v[50:53], v[78:81]
	v_mfma_f32_16x16x32_bf16 v[62:65], v[18:21], v[186:189], v[62:65]
	v_mfma_f32_16x16x32_bf16 v[10:13], v[18:21], v[194:197], v[10:13]
	v_mfma_f32_16x16x32_bf16 v[94:97], v[22:25], v[38:41], v[94:97]
	v_mfma_f32_16x16x32_bf16 v[90:93], v[82:85], v[34:37], v[90:93]
	v_mfma_f32_16x16x32_bf16 v[78:81], v[22:25], v[54:57], v[78:81]
	v_mfma_f32_16x16x32_bf16 v[74:77], v[82:85], v[50:53], v[74:77]
	v_mfma_f32_16x16x32_bf16 v[62:65], v[22:25], v[190:193], v[62:65]
	v_mfma_f32_16x16x32_bf16 v[58:61], v[82:85], v[186:189], v[58:61]
	v_mfma_f32_16x16x32_bf16 v[22:25], v[22:25], v[198:201], v[10:13]
	v_mfma_f32_16x16x32_bf16 v[10:13], v[82:85], v[194:197], v[14:17]
	v_mfma_f32_16x16x32_bf16 v[90:93], v[86:89], v[38:41], v[90:93]
	v_mfma_f32_16x16x32_bf16 v[74:77], v[86:89], v[54:57], v[74:77]
	v_mfma_f32_16x16x32_bf16 v[58:61], v[86:89], v[190:193], v[58:61]
	v_mfma_f32_16x16x32_bf16 v[18:21], v[86:89], v[198:201], v[10:13]
	v_mfma_f32_16x16x32_bf16 v[10:13], v[210:213], v[34:37], v[26:29]
	v_mfma_f32_16x16x32_bf16 v[86:89], v[214:217], v[38:41], v[10:13]
	v_mfma_f32_16x16x32_bf16 v[10:13], v[218:221], v[34:37], v[30:33]
	v_mfma_f32_16x16x32_bf16 v[82:85], v[234:237], v[38:41], v[10:13]
	v_mfma_f32_16x16x32_bf16 v[10:13], v[210:213], v[50:53], v[70:73]
	v_mfma_f32_16x16x32_bf16 v[70:73], v[214:217], v[54:57], v[10:13]
	v_mfma_f32_16x16x32_bf16 v[10:13], v[218:221], v[50:53], v[66:69]
	v_mfma_f32_16x16x32_bf16 v[66:69], v[234:237], v[54:57], v[10:13]
	v_mfma_f32_16x16x32_bf16 v[10:13], v[210:213], v[186:189], v[46:49]
	v_mfma_f32_16x16x32_bf16 v[46:49], v[214:217], v[190:193], v[10:13]
	v_mfma_f32_16x16x32_bf16 v[10:13], v[218:221], v[186:189], v[42:45]
	v_mfma_f32_16x16x32_bf16 v[6:9], v[210:213], v[194:197], v[6:9]
	v_mfma_f32_16x16x32_bf16 v[2:5], v[218:221], v[194:197], v[2:5]
	v_mfma_f32_16x16x32_bf16 v[42:45], v[234:237], v[190:193], v[10:13]
	v_mfma_f32_16x16x32_bf16 v[6:9], v[214:217], v[198:201], v[6:9]
	v_mfma_f32_16x16x32_bf16 v[2:5], v[234:237], v[198:201], v[2:5]
	s_add_i32 vcc_lo, vcc_lo, 2
	s_add_u32 s34, s34, 0x100
	s_addc_u32 s35, s35, 0
	s_add_u32 s56, s56, 0x100
	s_addc_u32 s57, s57, 0
	s_cmp_gt_u32 vcc_lo, 13

.LBB0_3261:
	s_add_u32 s0, s30, 0x9b00000
	s_addc_u32 s1, s31, 0
	s_add_u32 s4, s30, 0x1a51800
	s_addc_u32 s5, s31, 0
	s_add_u32 s48, s30, 0x10f000
	s_addc_u32 s49, s31, 0
	s_mov_b64 s[6:7], 0x80
	s_add_u32 s10, s34, 0x40080
	v_lshl_add_u64 v[2:3], v[2:3], 0, s[6:7]
	s_addc_u32 s11, s35, 0
	s_add_i32 m0, s43, 0x18000
	v_lshl_add_u64 v[4:5], v[4:5], 0, s[6:7]
	s_waitcnt vmcnt(0)
	s_barrier
	global_load_lds_dwordx4 v[2:3], off
	s_add_i32 m0, s43, 0x1a000
	s_add_i32 s50, s43, 0x8000
	v_lshl_add_u64 v[6:7], v[6:7], 0, s[6:7]
	global_load_lds_dwordx4 v[4:5], off
	s_mov_b32 m0, s50
	s_add_i32 s51, s43, 0xa000
	v_lshl_add_u64 v[8:9], v[8:9], 0, s[6:7]
	global_load_lds_dwordx4 v[6:7], off
	s_mov_b32 m0, s51
	s_waitcnt vmcnt(0)
	v_lshl_add_u64 v[14:15], s[10:11], 0, v[150:151]
	global_load_lds_dwordx4 v[8:9], off
	s_add_i32 m0, s43, 0x1c000
	v_lshl_add_u64 v[16:17], s[10:11], 0, v[146:147]
	global_load_lds_dwordx4 v[14:15], off
	s_add_i32 m0, s43, 0x1e000
	v_bfe_u32 v1, v170, 4, 2
	global_load_lds_dwordx4 v[16:17], off
	v_lshlrev_b32_e32 v3, 3, v1
	v_lshlrev_b32_e32 v4, 4, v1
	v_lshlrev_b32_e32 v1, 6, v170
	s_movk_i32 s9, 0x3c0
	s_sext_i32_i16 s17, s2
	s_and_b32 s2, s8, 3
	v_and_b32_e32 v2, 15, v170
	v_and_or_b32 v5, v1, s9, v4
	v_lshlrev_b32_e32 v1, 2, v170
	v_lshl_or_b32 v156, s2, 5, v3
	v_lshlrev_b32_e32 v3, 8, v170
	v_and_b32_e32 v6, 32, v1
	v_lshl_or_b32 v1, s3, 6, v2
	v_lshl_or_b32 v2, v2, 6, v4
	v_and_b32_e32 v3, 0x38000, v3
	v_lshlrev_b32_e32 v4, 11, v231
	v_or3_b32 v3, v11, v3, v4
	s_lshl_b32 s3, s3, 13
	v_add_u32_e32 v158, v3, v12
	v_lshlrev_b32_e32 v3, 4, v10
	v_bitop3_b32 v2, v2, s3, v6 bitop3:0xde
	s_lshl_b32 s3, s2, 12
	s_waitcnt vmcnt(6)
	v_and_b32_e32 v3, 0x78000, v3
	v_bitop3_b32 v157, s3, v5, v6 bitop3:0xf6
	v_or3_b32 v3, v11, v3, v4
	s_add_i32 s54, 0, 0x10000
	s_add_i32 s55, 0, 0x14000
	s_ashr_i32 s52, s22, 31
	s_mov_b32 s53, s22
	v_mov_b32_e32 v159, v155
	v_add_u32_e32 v160, v3, v12
	v_mov_b32_e32 v161, v155
	v_mov_b64_e32 v[162:163], 0xb00
	v_mov_b64_e32 v[164:165], 0xaff
	v_add_u32_e32 v171, s54, v157
	v_add_u32_e32 v173, 0, v2
	v_add_u32_e32 v177, s55, v157
	s_movk_i32 s56, 0x1600
	s_barrier
	global_load_dword v255, v[16:17], off
	global_load_dword v255, v[16:17], off
	global_load_dword v255, v[16:17], off
	global_load_dword v255, v[16:17], off
	global_load_dword v255, v[16:17], off
	global_load_dword v255, v[16:17], off
	global_load_dword v255, v[16:17], off
	global_load_dword v255, v[16:17], off

.LBB0_3264:
	s_ashr_i32 s11, s10, 31
	v_cmp_lt_i64_e32 vcc, s[12:13], v[162:163]
	s_lshl_b64 s[12:13], s[10:11], 19
	s_add_u32 s12, s36, s12
	s_addc_u32 s13, s37, s13
	s_and_b64 s[14:15], vcc, exec
	s_cselect_b32 s11, s13, s25
	s_cselect_b32 s57, s12, s24
	s_ashr_i32 s9, s8, 31
	s_lshl_b64 s[14:15], s[8:9], 19
	s_add_u32 s14, s38, s14
	s_addc_u32 s15, s39, s15
	s_and_b64 s[18:19], vcc, exec
	s_cselect_b32 s9, s15, s35
	s_cselect_b32 s60, s14, s34
	s_add_u32 s24, s24, 0x40080
	s_addc_u32 s25, s25, 0
	s_add_u32 s61, s34, 0x100
	s_addc_u32 s62, s35, 0
	s_mov_b32 s63, -2
	ds_read_b128 v[130:133], v171
	ds_read_b128 v[134:137], v171 offset:1024
	ds_read_b128 v[138:141], v171 offset:2048
	ds_read_b128 v[142:145], v171 offset:3072
	s_add_u32 s18, s24, 0xfffc0080
	s_addc_u32 s19, s25, -1
	s_cmp_eq_u32 s63, 12
	s_cselect_b32 s19, s11, s19
	s_cselect_b32 s18, s57, s18
	s_cselect_b32 s35, s9, s62
	s_cselect_b32 s34, s60, s61
	v_lshl_add_u64 v[174:175], s[24:25], 0, v[158:159]
	s_add_i32 m0, s43, 0xc000
	ds_read_b128 v[166:169], v173
	ds_read_b128 v[178:181], v173 offset:1024
	ds_read_b128 v[182:185], v173 offset:2048
	ds_read_b128 v[186:189], v173 offset:3072
	ds_read_b128 v[190:193], v173 offset:4096
	ds_read_b128 v[194:197], v173 offset:5120
	ds_read_b128 v[198:201], v173 offset:6144
	ds_read_b128 v[202:205], v173 offset:7168
	global_load_lds_dwordx4 v[174:175], off
	v_lshl_add_u64 v[174:175], s[24:25], 0, v[160:161]
	s_add_i32 m0, s43, 0xe000
	s_nop 0
	global_load_lds_dwordx4 v[174:175], off
	ds_read_b128 v[206:209], v177
	ds_read_b128 v[210:213], v177 offset:1024
	ds_read_b128 v[214:217], v177 offset:2048
	ds_read_b128 v[218:221], v177 offset:3072
	s_waitcnt lgkmcnt(0)
	s_setprio 1
	s_barrier
	v_mfma_f32_16x16x32_bf16 v[126:129], v[130:133], v[166:169], 0
	v_mfma_f32_16x16x32_bf16 v[122:125], v[138:141], v[166:169], 0
	v_mfma_f32_16x16x32_bf16 v[110:113], v[130:133], v[182:185], 0
	v_mfma_f32_16x16x32_bf16 v[106:109], v[138:141], v[182:185], 0
	v_mfma_f32_16x16x32_bf16 v[94:97], v[130:133], v[190:193], 0
	v_mfma_f32_16x16x32_bf16 v[90:93], v[138:141], v[190:193], 0
	v_mfma_f32_16x16x32_bf16 v[78:81], v[130:133], v[198:201], 0
	v_mfma_f32_16x16x32_bf16 v[74:77], v[138:141], v[198:201], 0
	v_mfma_f32_16x16x32_bf16 v[126:129], v[134:137], v[178:181], v[126:129]
	v_mfma_f32_16x16x32_bf16 v[122:125], v[142:145], v[178:181], v[122:125]
	v_mfma_f32_16x16x32_bf16 v[110:113], v[134:137], v[186:189], v[110:113]
	v_mfma_f32_16x16x32_bf16 v[106:109], v[142:145], v[186:189], v[106:109]
	v_mfma_f32_16x16x32_bf16 v[94:97], v[134:137], v[194:197], v[94:97]
	v_mfma_f32_16x16x32_bf16 v[90:93], v[142:145], v[194:197], v[90:93]
	v_mfma_f32_16x16x32_bf16 v[78:81], v[134:137], v[202:205], v[78:81]
	v_mfma_f32_16x16x32_bf16 v[74:77], v[142:145], v[202:205], v[74:77]
	v_mfma_f32_16x16x32_bf16 v[118:121], v[206:209], v[166:169], 0
	v_mfma_f32_16x16x32_bf16 v[114:117], v[214:217], v[166:169], 0
	v_mfma_f32_16x16x32_bf16 v[102:105], v[206:209], v[182:185], 0
	v_mfma_f32_16x16x32_bf16 v[98:101], v[214:217], v[182:185], 0
	v_mfma_f32_16x16x32_bf16 v[86:89], v[206:209], v[190:193], 0
	v_mfma_f32_16x16x32_bf16 v[82:85], v[214:217], v[190:193], 0
	v_mfma_f32_16x16x32_bf16 v[70:73], v[206:209], v[198:201], 0
	v_mfma_f32_16x16x32_bf16 v[66:69], v[214:217], v[198:201], 0
	v_mfma_f32_16x16x32_bf16 v[118:121], v[210:213], v[178:181], v[118:121]
	v_mfma_f32_16x16x32_bf16 v[114:117], v[218:221], v[178:181], v[114:117]
	v_mfma_f32_16x16x32_bf16 v[102:105], v[210:213], v[186:189], v[102:105]
	v_mfma_f32_16x16x32_bf16 v[98:101], v[218:221], v[186:189], v[98:101]
	v_mfma_f32_16x16x32_bf16 v[86:89], v[210:213], v[194:197], v[86:89]
	v_mfma_f32_16x16x32_bf16 v[82:85], v[218:221], v[194:197], v[82:85]
	v_mfma_f32_16x16x32_bf16 v[70:73], v[210:213], v[202:205], v[70:73]
	v_mfma_f32_16x16x32_bf16 v[66:69], v[218:221], v[202:205], v[66:69]
	s_barrier
	s_setprio 0
	s_add_i32 s20, s54, s42
	v_lshl_add_u64 v[174:175], s[34:35], 0, v[150:151]
	s_mov_b32 m0, s20
	s_nop 0
	global_load_lds_dwordx4 v[174:175], off
	v_lshl_add_u64 v[222:223], s[34:35], 0, v[146:147]
	s_add_i32 m0, s20, 0x2000
	s_nop 0
	global_load_lds_dwordx4 v[222:223], off
	s_mov_b32 m0, s43
	v_lshl_add_u64 v[224:225], s[18:19], 0, v[152:153]
	ds_read_b128 v[166:169], v173 offset:16384
	ds_read_b128 v[178:181], v173 offset:17408
	ds_read_b128 v[182:185], v173 offset:18432
	ds_read_b128 v[186:189], v173 offset:19456
	ds_read_b128 v[190:193], v173 offset:20480
	ds_read_b128 v[194:197], v173 offset:21504
	ds_read_b128 v[198:201], v173 offset:22528
	ds_read_b128 v[202:205], v173 offset:23552
	global_load_lds_dwordx4 v[224:225], off
	v_lshl_add_u64 v[226:227], s[18:19], 0, v[148:149]
	s_mov_b32 m0, s44
	s_nop 0
	global_load_lds_dwordx4 v[226:227], off
	s_waitcnt vmcnt(14)
	s_waitcnt lgkmcnt(0)
	s_setprio 1
	s_barrier
	v_mfma_f32_16x16x32_bf16 v[62:65], v[130:133], v[166:169], 0
	v_mfma_f32_16x16x32_bf16 v[58:61], v[138:141], v[166:169], 0
	v_mfma_f32_16x16x32_bf16 v[46:49], v[130:133], v[182:185], 0
	v_mfma_f32_16x16x32_bf16 v[42:45], v[138:141], v[182:185], 0
	v_mfma_f32_16x16x32_bf16 v[30:33], v[130:133], v[190:193], 0
	v_mfma_f32_16x16x32_bf16 v[26:29], v[138:141], v[190:193], 0
	v_mfma_f32_16x16x32_bf16 v[14:17], v[130:133], v[198:201], 0
	v_mfma_f32_16x16x32_bf16 v[10:13], v[138:141], v[198:201], 0
	v_mfma_f32_16x16x32_bf16 v[62:65], v[134:137], v[178:181], v[62:65]
	v_mfma_f32_16x16x32_bf16 v[58:61], v[142:145], v[178:181], v[58:61]
	v_mfma_f32_16x16x32_bf16 v[46:49], v[134:137], v[186:189], v[46:49]
	v_mfma_f32_16x16x32_bf16 v[42:45], v[142:145], v[186:189], v[42:45]
	v_mfma_f32_16x16x32_bf16 v[30:33], v[134:137], v[194:197], v[30:33]
	v_mfma_f32_16x16x32_bf16 v[26:29], v[142:145], v[194:197], v[26:29]
	v_mfma_f32_16x16x32_bf16 v[14:17], v[134:137], v[202:205], v[14:17]
	v_mfma_f32_16x16x32_bf16 v[10:13], v[142:145], v[202:205], v[10:13]
	v_mfma_f32_16x16x32_bf16 v[54:57], v[206:209], v[166:169], 0
	v_mfma_f32_16x16x32_bf16 v[50:53], v[214:217], v[166:169], 0
	v_mfma_f32_16x16x32_bf16 v[38:41], v[206:209], v[182:185], 0
	v_mfma_f32_16x16x32_bf16 v[34:37], v[214:217], v[182:185], 0
	v_mfma_f32_16x16x32_bf16 v[22:25], v[206:209], v[190:193], 0
	v_mfma_f32_16x16x32_bf16 v[18:21], v[214:217], v[190:193], 0
	v_mfma_f32_16x16x32_bf16 v[6:9], v[206:209], v[198:201], 0
	v_mfma_f32_16x16x32_bf16 v[2:5], v[214:217], v[198:201], 0
	v_mfma_f32_16x16x32_bf16 v[54:57], v[210:213], v[178:181], v[54:57]
	v_mfma_f32_16x16x32_bf16 v[50:53], v[218:221], v[178:181], v[50:53]
	v_mfma_f32_16x16x32_bf16 v[38:41], v[210:213], v[186:189], v[38:41]
	v_mfma_f32_16x16x32_bf16 v[34:37], v[218:221], v[186:189], v[34:37]
	v_mfma_f32_16x16x32_bf16 v[22:25], v[210:213], v[194:197], v[22:25]
	v_mfma_f32_16x16x32_bf16 v[18:21], v[218:221], v[194:197], v[18:21]
	v_mfma_f32_16x16x32_bf16 v[6:9], v[210:213], v[202:205], v[6:9]
	v_mfma_f32_16x16x32_bf16 v[2:5], v[218:221], v[202:205], v[2:5]
	s_barrier
	s_setprio 0
	s_add_u32 s20, s34, 0x40000
	s_addc_u32 s21, s35, 0
	s_add_i32 s64, s55, s42
	v_lshl_add_u64 v[246:247], s[20:21], 0, v[150:151]
	s_mov_b32 m0, s64
	s_nop 0
	global_load_lds_dwordx4 v[246:247], off
	v_lshl_add_u64 v[246:247], s[20:21], 0, v[146:147]
	s_add_i32 m0, s64, 0x2000
	s_nop 0
	global_load_lds_dwordx4 v[246:247], off
	s_add_i32 s20, 0, 0x18000
	v_add_u32_e32 v142, s20, v157
	ds_read_b128 v[130:133], v142
	ds_read_b128 v[134:137], v142 offset:1024
	ds_read_b128 v[138:141], v142 offset:2048
	ds_read_b128 v[142:145], v142 offset:3072
	s_add_u32 s18, s18, 0x40000
	s_addc_u32 s19, s19, 0
	s_mov_b32 m0, s45
	v_lshl_add_u64 v[206:207], s[18:19], 0, v[152:153]
	ds_read_b128 v[166:169], v173 offset:32768
	ds_read_b128 v[178:181], v173 offset:33792
	ds_read_b128 v[182:185], v173 offset:34816
	ds_read_b128 v[186:189], v173 offset:35840
	ds_read_b128 v[190:193], v173 offset:36864
	ds_read_b128 v[194:197], v173 offset:37888
	ds_read_b128 v[198:201], v173 offset:38912
	ds_read_b128 v[202:205], v173 offset:39936
	global_load_lds_dwordx4 v[206:207], off
	v_lshl_add_u64 v[206:207], s[18:19], 0, v[148:149]
	s_mov_b32 m0, s46
	s_nop 0
	global_load_lds_dwordx4 v[206:207], off
	s_add_i32 s21, 0, 0x1c000
	v_add_u32_e32 v154, s21, v157
	ds_read_b128 v[206:209], v154
	ds_read_b128 v[210:213], v154 offset:1024
	ds_read_b128 v[214:217], v154 offset:2048
	ds_read_b128 v[218:221], v154 offset:3072
	s_waitcnt vmcnt(8)
	s_waitcnt lgkmcnt(0)
	s_setprio 1
	s_barrier
	v_mfma_f32_16x16x32_bf16 v[126:129], v[130:133], v[166:169], v[126:129]
	v_mfma_f32_16x16x32_bf16 v[122:125], v[138:141], v[166:169], v[122:125]
	v_mfma_f32_16x16x32_bf16 v[110:113], v[130:133], v[182:185], v[110:113]
	v_mfma_f32_16x16x32_bf16 v[106:109], v[138:141], v[182:185], v[106:109]
	v_mfma_f32_16x16x32_bf16 v[94:97], v[130:133], v[190:193], v[94:97]
	v_mfma_f32_16x16x32_bf16 v[90:93], v[138:141], v[190:193], v[90:93]
	v_mfma_f32_16x16x32_bf16 v[78:81], v[130:133], v[198:201], v[78:81]
	v_mfma_f32_16x16x32_bf16 v[74:77], v[138:141], v[198:201], v[74:77]
	v_mfma_f32_16x16x32_bf16 v[126:129], v[134:137], v[178:181], v[126:129]
	v_mfma_f32_16x16x32_bf16 v[122:125], v[142:145], v[178:181], v[122:125]
	v_mfma_f32_16x16x32_bf16 v[110:113], v[134:137], v[186:189], v[110:113]
	v_mfma_f32_16x16x32_bf16 v[106:109], v[142:145], v[186:189], v[106:109]
	v_mfma_f32_16x16x32_bf16 v[94:97], v[134:137], v[194:197], v[94:97]
	v_mfma_f32_16x16x32_bf16 v[90:93], v[142:145], v[194:197], v[90:93]
	v_mfma_f32_16x16x32_bf16 v[78:81], v[134:137], v[202:205], v[78:81]
	v_mfma_f32_16x16x32_bf16 v[74:77], v[142:145], v[202:205], v[74:77]
	v_mfma_f32_16x16x32_bf16 v[118:121], v[206:209], v[166:169], v[118:121]
	v_mfma_f32_16x16x32_bf16 v[114:117], v[214:217], v[166:169], v[114:117]
	v_mfma_f32_16x16x32_bf16 v[102:105], v[206:209], v[182:185], v[102:105]
	v_mfma_f32_16x16x32_bf16 v[98:101], v[214:217], v[182:185], v[98:101]
	v_mfma_f32_16x16x32_bf16 v[86:89], v[206:209], v[190:193], v[86:89]
	v_mfma_f32_16x16x32_bf16 v[82:85], v[214:217], v[190:193], v[82:85]
	v_mfma_f32_16x16x32_bf16 v[70:73], v[206:209], v[198:201], v[70:73]
	v_mfma_f32_16x16x32_bf16 v[66:69], v[214:217], v[198:201], v[66:69]
	v_mfma_f32_16x16x32_bf16 v[118:121], v[210:213], v[178:181], v[118:121]
	v_mfma_f32_16x16x32_bf16 v[114:117], v[218:221], v[178:181], v[114:117]
	v_mfma_f32_16x16x32_bf16 v[102:105], v[210:213], v[186:189], v[102:105]
	v_mfma_f32_16x16x32_bf16 v[98:101], v[218:221], v[186:189], v[98:101]
	v_mfma_f32_16x16x32_bf16 v[86:89], v[210:213], v[194:197], v[86:89]
	v_mfma_f32_16x16x32_bf16 v[82:85], v[218:221], v[194:197], v[82:85]
	v_mfma_f32_16x16x32_bf16 v[70:73], v[210:213], v[202:205], v[70:73]
	v_mfma_f32_16x16x32_bf16 v[66:69], v[218:221], v[202:205], v[66:69]
	s_barrier
	s_setprio 0
	s_add_i32 s18, s20, s42
	v_lshl_add_u64 v[174:175], v[174:175], 0, s[6:7]
	s_mov_b32 m0, s18
	s_nop 0
	global_load_lds_dwordx4 v[174:175], off
	v_lshl_add_u64 v[174:175], v[222:223], 0, s[6:7]
	s_add_i32 m0, s18, 0x2000
	s_nop 0
	global_load_lds_dwordx4 v[174:175], off
	s_mov_b32 m0, s50
	v_lshl_add_u64 v[174:175], v[224:225], 0, s[6:7]
	ds_read_b128 v[166:169], v173 offset:49152
	ds_read_b128 v[178:181], v173 offset:50176
	ds_read_b128 v[182:185], v173 offset:51200
	ds_read_b128 v[186:189], v173 offset:52224
	ds_read_b128 v[190:193], v173 offset:53248
	ds_read_b128 v[194:197], v173 offset:54272
	ds_read_b128 v[198:201], v173 offset:55296
	ds_read_b128 v[202:205], v173 offset:56320
	global_load_lds_dwordx4 v[174:175], off
	v_lshl_add_u64 v[174:175], v[226:227], 0, s[6:7]
	s_mov_b32 m0, s51
	s_nop 0
	global_load_lds_dwordx4 v[174:175], off
	s_add_u32 s18, s34, 0x40080
	s_addc_u32 s19, s35, 0
	s_add_i32 s20, s21, s42
	v_lshl_add_u64 v[248:249], s[18:19], 0, v[150:151]
	s_mov_b32 m0, s20
	s_nop 0
	global_load_lds_dwordx4 v[248:249], off
	v_lshl_add_u64 v[248:249], s[18:19], 0, v[146:147]
	s_add_i32 m0, s20, 0x2000
	s_nop 0
	global_load_lds_dwordx4 v[248:249], off
	s_waitcnt vmcnt(6)
	s_waitcnt lgkmcnt(0)
	s_setprio 1
	s_barrier
	v_mfma_f32_16x16x32_bf16 v[62:65], v[130:133], v[166:169], v[62:65]
	v_mfma_f32_16x16x32_bf16 v[58:61], v[138:141], v[166:169], v[58:61]
	v_mfma_f32_16x16x32_bf16 v[46:49], v[130:133], v[182:185], v[46:49]
	v_mfma_f32_16x16x32_bf16 v[42:45], v[138:141], v[182:185], v[42:45]
	v_mfma_f32_16x16x32_bf16 v[30:33], v[130:133], v[190:193], v[30:33]
	v_mfma_f32_16x16x32_bf16 v[26:29], v[138:141], v[190:193], v[26:29]
	v_mfma_f32_16x16x32_bf16 v[14:17], v[130:133], v[198:201], v[14:17]
	v_mfma_f32_16x16x32_bf16 v[10:13], v[138:141], v[198:201], v[10:13]
	v_mfma_f32_16x16x32_bf16 v[62:65], v[134:137], v[178:181], v[62:65]
	v_mfma_f32_16x16x32_bf16 v[58:61], v[142:145], v[178:181], v[58:61]
	v_mfma_f32_16x16x32_bf16 v[46:49], v[134:137], v[186:189], v[46:49]
	v_mfma_f32_16x16x32_bf16 v[42:45], v[142:145], v[186:189], v[42:45]
	v_mfma_f32_16x16x32_bf16 v[30:33], v[134:137], v[194:197], v[30:33]
	v_mfma_f32_16x16x32_bf16 v[26:29], v[142:145], v[194:197], v[26:29]
	v_mfma_f32_16x16x32_bf16 v[14:17], v[134:137], v[202:205], v[14:17]
	v_mfma_f32_16x16x32_bf16 v[10:13], v[142:145], v[202:205], v[10:13]
	v_mfma_f32_16x16x32_bf16 v[54:57], v[206:209], v[166:169], v[54:57]
	v_mfma_f32_16x16x32_bf16 v[50:53], v[214:217], v[166:169], v[50:53]
	v_mfma_f32_16x16x32_bf16 v[38:41], v[206:209], v[182:185], v[38:41]
	v_mfma_f32_16x16x32_bf16 v[34:37], v[214:217], v[182:185], v[34:37]
	v_mfma_f32_16x16x32_bf16 v[22:25], v[206:209], v[190:193], v[22:25]
	v_mfma_f32_16x16x32_bf16 v[18:21], v[214:217], v[190:193], v[18:21]
	v_mfma_f32_16x16x32_bf16 v[6:9], v[206:209], v[198:201], v[6:9]
	v_mfma_f32_16x16x32_bf16 v[2:5], v[214:217], v[198:201], v[2:5]
	v_mfma_f32_16x16x32_bf16 v[54:57], v[210:213], v[178:181], v[54:57]
	v_mfma_f32_16x16x32_bf16 v[50:53], v[218:221], v[178:181], v[50:53]
	v_mfma_f32_16x16x32_bf16 v[38:41], v[210:213], v[186:189], v[38:41]
	v_mfma_f32_16x16x32_bf16 v[34:37], v[218:221], v[186:189], v[34:37]
	v_mfma_f32_16x16x32_bf16 v[22:25], v[210:213], v[194:197], v[22:25]
	v_mfma_f32_16x16x32_bf16 v[18:21], v[218:221], v[194:197], v[18:21]
	v_mfma_f32_16x16x32_bf16 v[6:9], v[210:213], v[202:205], v[6:9]
	v_mfma_f32_16x16x32_bf16 v[2:5], v[218:221], v[202:205], v[2:5]
	s_add_i32 s63, s63, 2
	s_add_u32 s24, s24, 0x100
	s_addc_u32 s25, s25, 0
	s_add_u32 s61, s61, 0x100
	s_addc_u32 s62, s62, 0
	s_cmp_gt_u32 s63, 13
